# lean version with the substitution rows fetched in batches (12 LDS round trips instead of 31)
# baseline (speedup 1.0000x reference)
.Ldc_b2:
	s_waitcnt lgkmcnt(0)
	s_barrier
	s_cmp_ge_u32 s60, 2
	s_cbranch_scc1 .Ldc_s2q
	s_cmp_eq_u32 s60, 1
	s_cbranch_scc1 .Ldc_s2k
	s_mov_b32 exec_hi, 0
	v_and_b32_e32 v135, 31, v221
	v_lshlrev_b32_e32 v135, 2, v135
	v_add_u32_e32 v135, 0xe200, v135
	v_add_u32_e32 v245, 0x480, v135
	v_add_u32_e32 v246, 0x900, v135
	v_add_u32_e32 v247, 0xd80, v135
	ds_read2_b32 v[10:11], v135 offset0:0 offset1:36
	ds_read2_b32 v[12:13], v135 offset0:72 offset1:108
	ds_read2_b32 v[14:15], v135 offset0:144 offset1:180
	ds_read2_b32 v[16:17], v135 offset0:216 offset1:252
	ds_read2_b32 v[18:19], v245 offset0:0 offset1:36
	ds_read2_b32 v[20:21], v245 offset0:72 offset1:108
	ds_read2_b32 v[22:23], v245 offset0:144 offset1:180
	ds_read2_b32 v[24:25], v245 offset0:216 offset1:252
	ds_read2_b32 v[26:27], v246 offset0:0 offset1:36
	ds_read2_b32 v[28:29], v246 offset0:72 offset1:108
	ds_read2_b32 v[30:31], v246 offset0:144 offset1:180
	ds_read2_b32 v[32:33], v246 offset0:216 offset1:252
	ds_read2_b32 v[34:35], v247 offset0:0 offset1:36
	ds_read2_b32 v[36:37], v247 offset0:72 offset1:108
	ds_read2_b32 v[38:39], v247 offset0:144 offset1:180
	ds_read2_b32 v[40:41], v247 offset0:216 offset1:252
	ds_read_b128 v[42:45], v1 offset:44032
	ds_read_b128 v[46:49], v1 offset:44048
	ds_read_b128 v[50:53], v1 offset:44064
	ds_read_b128 v[54:57], v1 offset:44080
	ds_read_b128 v[58:61], v1 offset:44096
	ds_read_b128 v[62:65], v1 offset:44112
	ds_read_b128 v[66:69], v1 offset:44128
	ds_read_b128 v[70:73], v1 offset:44144
	s_waitcnt lgkmcnt(0)
	v_fmac_f32_e32 v11, v43, v10
	v_pk_fma_f32 v[12:13], v[44:45], v[10:11], v[12:13] op_sel:[0,0,0] op_sel_hi:[1,0,1]
	v_pk_fma_f32 v[14:15], v[46:47], v[10:11], v[14:15] op_sel:[0,0,0] op_sel_hi:[1,0,1]
	v_pk_fma_f32 v[16:17], v[48:49], v[10:11], v[16:17] op_sel:[0,0,0] op_sel_hi:[1,0,1]
	v_pk_fma_f32 v[18:19], v[50:51], v[10:11], v[18:19] op_sel:[0,0,0] op_sel_hi:[1,0,1]
	v_pk_fma_f32 v[20:21], v[52:53], v[10:11], v[20:21] op_sel:[0,0,0] op_sel_hi:[1,0,1]
	v_pk_fma_f32 v[22:23], v[54:55], v[10:11], v[22:23] op_sel:[0,0,0] op_sel_hi:[1,0,1]
	v_pk_fma_f32 v[24:25], v[56:57], v[10:11], v[24:25] op_sel:[0,0,0] op_sel_hi:[1,0,1]
	v_pk_fma_f32 v[26:27], v[58:59], v[10:11], v[26:27] op_sel:[0,0,0] op_sel_hi:[1,0,1]
	v_pk_fma_f32 v[28:29], v[60:61], v[10:11], v[28:29] op_sel:[0,0,0] op_sel_hi:[1,0,1]
	v_pk_fma_f32 v[30:31], v[62:63], v[10:11], v[30:31] op_sel:[0,0,0] op_sel_hi:[1,0,1]
	v_pk_fma_f32 v[32:33], v[64:65], v[10:11], v[32:33] op_sel:[0,0,0] op_sel_hi:[1,0,1]
	v_pk_fma_f32 v[34:35], v[66:67], v[10:11], v[34:35] op_sel:[0,0,0] op_sel_hi:[1,0,1]
	v_pk_fma_f32 v[36:37], v[68:69], v[10:11], v[36:37] op_sel:[0,0,0] op_sel_hi:[1,0,1]
	v_pk_fma_f32 v[38:39], v[70:71], v[10:11], v[38:39] op_sel:[0,0,0] op_sel_hi:[1,0,1]
	v_pk_fma_f32 v[40:41], v[72:73], v[10:11], v[40:41] op_sel:[0,0,0] op_sel_hi:[1,0,1]
	ds_read_b128 v[42:45], v1 offset:44176
	ds_read_b128 v[46:49], v1 offset:44192
	ds_read_b128 v[50:53], v1 offset:44208
	ds_read_b128 v[54:57], v1 offset:44224
	ds_read_b128 v[58:61], v1 offset:44240
	ds_read_b128 v[62:65], v1 offset:44256
	ds_read_b128 v[66:69], v1 offset:44272
	ds_read_b128 v[70:73], v1 offset:44288
	s_waitcnt lgkmcnt(0)
	v_pk_fma_f32 v[12:13], v[44:45], v[10:11], v[12:13] op_sel:[0,1,0] op_sel_hi:[1,1,1]
	v_pk_fma_f32 v[14:15], v[46:47], v[10:11], v[14:15] op_sel:[0,1,0] op_sel_hi:[1,1,1]
	v_pk_fma_f32 v[16:17], v[48:49], v[10:11], v[16:17] op_sel:[0,1,0] op_sel_hi:[1,1,1]
	v_pk_fma_f32 v[18:19], v[50:51], v[10:11], v[18:19] op_sel:[0,1,0] op_sel_hi:[1,1,1]
	v_pk_fma_f32 v[20:21], v[52:53], v[10:11], v[20:21] op_sel:[0,1,0] op_sel_hi:[1,1,1]
	v_pk_fma_f32 v[22:23], v[54:55], v[10:11], v[22:23] op_sel:[0,1,0] op_sel_hi:[1,1,1]
	v_pk_fma_f32 v[24:25], v[56:57], v[10:11], v[24:25] op_sel:[0,1,0] op_sel_hi:[1,1,1]
	v_pk_fma_f32 v[26:27], v[58:59], v[10:11], v[26:27] op_sel:[0,1,0] op_sel_hi:[1,1,1]
	v_pk_fma_f32 v[28:29], v[60:61], v[10:11], v[28:29] op_sel:[0,1,0] op_sel_hi:[1,1,1]
	v_pk_fma_f32 v[30:31], v[62:63], v[10:11], v[30:31] op_sel:[0,1,0] op_sel_hi:[1,1,1]
	v_pk_fma_f32 v[32:33], v[64:65], v[10:11], v[32:33] op_sel:[0,1,0] op_sel_hi:[1,1,1]
	v_pk_fma_f32 v[34:35], v[66:67], v[10:11], v[34:35] op_sel:[0,1,0] op_sel_hi:[1,1,1]
	v_pk_fma_f32 v[36:37], v[68:69], v[10:11], v[36:37] op_sel:[0,1,0] op_sel_hi:[1,1,1]
	v_pk_fma_f32 v[38:39], v[70:71], v[10:11], v[38:39] op_sel:[0,1,0] op_sel_hi:[1,1,1]
	v_pk_fma_f32 v[40:41], v[72:73], v[10:11], v[40:41] op_sel:[0,1,0] op_sel_hi:[1,1,1]
	ds_read_b128 v[42:45], v1 offset:44320
	ds_read_b128 v[46:49], v1 offset:44336
	ds_read_b128 v[50:53], v1 offset:44352
	ds_read_b128 v[54:57], v1 offset:44368
	ds_read_b128 v[58:61], v1 offset:44384
	ds_read_b128 v[62:65], v1 offset:44400
	ds_read_b128 v[66:69], v1 offset:44416
	ds_read_b128 v[70:73], v1 offset:44432
	ds_read_b128 v[74:77], v1 offset:44480
	ds_read_b128 v[78:81], v1 offset:44496
	ds_read_b128 v[82:85], v1 offset:44512
	ds_read_b128 v[86:89], v1 offset:44528
	ds_read_b128 v[226:229], v1 offset:44544
	ds_read_b128 v[230:233], v1 offset:44560
	ds_read_b128 v[234:237], v1 offset:44576
	s_waitcnt lgkmcnt(0)
	v_fmac_f32_e32 v13, v45, v12
	v_pk_fma_f32 v[14:15], v[46:47], v[12:13], v[14:15] op_sel:[0,0,0] op_sel_hi:[1,0,1]
	v_pk_fma_f32 v[16:17], v[48:49], v[12:13], v[16:17] op_sel:[0,0,0] op_sel_hi:[1,0,1]
	v_pk_fma_f32 v[18:19], v[50:51], v[12:13], v[18:19] op_sel:[0,0,0] op_sel_hi:[1,0,1]
	v_pk_fma_f32 v[20:21], v[52:53], v[12:13], v[20:21] op_sel:[0,0,0] op_sel_hi:[1,0,1]
	v_pk_fma_f32 v[22:23], v[54:55], v[12:13], v[22:23] op_sel:[0,0,0] op_sel_hi:[1,0,1]
	v_pk_fma_f32 v[24:25], v[56:57], v[12:13], v[24:25] op_sel:[0,0,0] op_sel_hi:[1,0,1]
	v_pk_fma_f32 v[26:27], v[58:59], v[12:13], v[26:27] op_sel:[0,0,0] op_sel_hi:[1,0,1]
	v_pk_fma_f32 v[28:29], v[60:61], v[12:13], v[28:29] op_sel:[0,0,0] op_sel_hi:[1,0,1]
	v_pk_fma_f32 v[30:31], v[62:63], v[12:13], v[30:31] op_sel:[0,0,0] op_sel_hi:[1,0,1]
	v_pk_fma_f32 v[32:33], v[64:65], v[12:13], v[32:33] op_sel:[0,0,0] op_sel_hi:[1,0,1]
	v_pk_fma_f32 v[34:35], v[66:67], v[12:13], v[34:35] op_sel:[0,0,0] op_sel_hi:[1,0,1]
	v_pk_fma_f32 v[36:37], v[68:69], v[12:13], v[36:37] op_sel:[0,0,0] op_sel_hi:[1,0,1]
	v_pk_fma_f32 v[38:39], v[70:71], v[12:13], v[38:39] op_sel:[0,0,0] op_sel_hi:[1,0,1]
	v_pk_fma_f32 v[40:41], v[72:73], v[12:13], v[40:41] op_sel:[0,0,0] op_sel_hi:[1,0,1]
	v_pk_fma_f32 v[14:15], v[74:75], v[12:13], v[14:15] op_sel:[0,1,0] op_sel_hi:[1,1,1]
	v_pk_fma_f32 v[16:17], v[76:77], v[12:13], v[16:17] op_sel:[0,1,0] op_sel_hi:[1,1,1]
	v_pk_fma_f32 v[18:19], v[78:79], v[12:13], v[18:19] op_sel:[0,1,0] op_sel_hi:[1,1,1]
	v_pk_fma_f32 v[20:21], v[80:81], v[12:13], v[20:21] op_sel:[0,1,0] op_sel_hi:[1,1,1]
	v_pk_fma_f32 v[22:23], v[82:83], v[12:13], v[22:23] op_sel:[0,1,0] op_sel_hi:[1,1,1]
	v_pk_fma_f32 v[24:25], v[84:85], v[12:13], v[24:25] op_sel:[0,1,0] op_sel_hi:[1,1,1]
	v_pk_fma_f32 v[26:27], v[86:87], v[12:13], v[26:27] op_sel:[0,1,0] op_sel_hi:[1,1,1]
	v_pk_fma_f32 v[28:29], v[88:89], v[12:13], v[28:29] op_sel:[0,1,0] op_sel_hi:[1,1,1]
	v_pk_fma_f32 v[30:31], v[226:227], v[12:13], v[30:31] op_sel:[0,1,0] op_sel_hi:[1,1,1]
	v_pk_fma_f32 v[32:33], v[228:229], v[12:13], v[32:33] op_sel:[0,1,0] op_sel_hi:[1,1,1]
	v_pk_fma_f32 v[34:35], v[230:231], v[12:13], v[34:35] op_sel:[0,1,0] op_sel_hi:[1,1,1]
	v_pk_fma_f32 v[36:37], v[232:233], v[12:13], v[36:37] op_sel:[0,1,0] op_sel_hi:[1,1,1]
	v_pk_fma_f32 v[38:39], v[234:235], v[12:13], v[38:39] op_sel:[0,1,0] op_sel_hi:[1,1,1]
	v_pk_fma_f32 v[40:41], v[236:237], v[12:13], v[40:41] op_sel:[0,1,0] op_sel_hi:[1,1,1]
	ds_read_b128 v[42:45], v1 offset:44624
	ds_read_b128 v[46:49], v1 offset:44640
	ds_read_b128 v[50:53], v1 offset:44656
	ds_read_b128 v[54:57], v1 offset:44672
	ds_read_b128 v[58:61], v1 offset:44688
	ds_read_b128 v[62:65], v1 offset:44704
	ds_read_b128 v[66:69], v1 offset:44720
	ds_read_b128 v[70:73], v1 offset:44768
	ds_read_b128 v[74:77], v1 offset:44784
	ds_read_b128 v[78:81], v1 offset:44800
	ds_read_b128 v[82:85], v1 offset:44816
	ds_read_b128 v[86:89], v1 offset:44832
	ds_read_b128 v[226:229], v1 offset:44848
	ds_read_b128 v[230:233], v1 offset:44864
	s_waitcnt lgkmcnt(0)
	v_fmac_f32_e32 v15, v43, v14
	v_pk_fma_f32 v[16:17], v[44:45], v[14:15], v[16:17] op_sel:[0,0,0] op_sel_hi:[1,0,1]
	v_pk_fma_f32 v[18:19], v[46:47], v[14:15], v[18:19] op_sel:[0,0,0] op_sel_hi:[1,0,1]
	v_pk_fma_f32 v[20:21], v[48:49], v[14:15], v[20:21] op_sel:[0,0,0] op_sel_hi:[1,0,1]
	v_pk_fma_f32 v[22:23], v[50:51], v[14:15], v[22:23] op_sel:[0,0,0] op_sel_hi:[1,0,1]
	v_pk_fma_f32 v[24:25], v[52:53], v[14:15], v[24:25] op_sel:[0,0,0] op_sel_hi:[1,0,1]
	v_pk_fma_f32 v[26:27], v[54:55], v[14:15], v[26:27] op_sel:[0,0,0] op_sel_hi:[1,0,1]
	v_pk_fma_f32 v[28:29], v[56:57], v[14:15], v[28:29] op_sel:[0,0,0] op_sel_hi:[1,0,1]
	v_pk_fma_f32 v[30:31], v[58:59], v[14:15], v[30:31] op_sel:[0,0,0] op_sel_hi:[1,0,1]
	v_pk_fma_f32 v[32:33], v[60:61], v[14:15], v[32:33] op_sel:[0,0,0] op_sel_hi:[1,0,1]
	v_pk_fma_f32 v[34:35], v[62:63], v[14:15], v[34:35] op_sel:[0,0,0] op_sel_hi:[1,0,1]
	v_pk_fma_f32 v[36:37], v[64:65], v[14:15], v[36:37] op_sel:[0,0,0] op_sel_hi:[1,0,1]
	v_pk_fma_f32 v[38:39], v[66:67], v[14:15], v[38:39] op_sel:[0,0,0] op_sel_hi:[1,0,1]
	v_pk_fma_f32 v[40:41], v[68:69], v[14:15], v[40:41] op_sel:[0,0,0] op_sel_hi:[1,0,1]
	v_pk_fma_f32 v[16:17], v[72:73], v[14:15], v[16:17] op_sel:[0,1,0] op_sel_hi:[1,1,1]
	v_pk_fma_f32 v[18:19], v[74:75], v[14:15], v[18:19] op_sel:[0,1,0] op_sel_hi:[1,1,1]
	v_pk_fma_f32 v[20:21], v[76:77], v[14:15], v[20:21] op_sel:[0,1,0] op_sel_hi:[1,1,1]
	v_pk_fma_f32 v[22:23], v[78:79], v[14:15], v[22:23] op_sel:[0,1,0] op_sel_hi:[1,1,1]
	v_pk_fma_f32 v[24:25], v[80:81], v[14:15], v[24:25] op_sel:[0,1,0] op_sel_hi:[1,1,1]
	v_pk_fma_f32 v[26:27], v[82:83], v[14:15], v[26:27] op_sel:[0,1,0] op_sel_hi:[1,1,1]
	v_pk_fma_f32 v[28:29], v[84:85], v[14:15], v[28:29] op_sel:[0,1,0] op_sel_hi:[1,1,1]
	v_pk_fma_f32 v[30:31], v[86:87], v[14:15], v[30:31] op_sel:[0,1,0] op_sel_hi:[1,1,1]
	v_pk_fma_f32 v[32:33], v[88:89], v[14:15], v[32:33] op_sel:[0,1,0] op_sel_hi:[1,1,1]
	v_pk_fma_f32 v[34:35], v[226:227], v[14:15], v[34:35] op_sel:[0,1,0] op_sel_hi:[1,1,1]
	v_pk_fma_f32 v[36:37], v[228:229], v[14:15], v[36:37] op_sel:[0,1,0] op_sel_hi:[1,1,1]
	v_pk_fma_f32 v[38:39], v[230:231], v[14:15], v[38:39] op_sel:[0,1,0] op_sel_hi:[1,1,1]
	v_pk_fma_f32 v[40:41], v[232:233], v[14:15], v[40:41] op_sel:[0,1,0] op_sel_hi:[1,1,1]
	ds_read_b128 v[42:45], v1 offset:44912
	ds_read_b128 v[46:49], v1 offset:44928
	ds_read_b128 v[50:53], v1 offset:44944
	ds_read_b128 v[54:57], v1 offset:44960
	ds_read_b128 v[58:61], v1 offset:44976
	ds_read_b128 v[62:65], v1 offset:44992
	ds_read_b128 v[66:69], v1 offset:45008
	ds_read_b128 v[70:73], v1 offset:45072
	ds_read_b128 v[74:77], v1 offset:45088
	ds_read_b128 v[78:81], v1 offset:45104
	ds_read_b128 v[82:85], v1 offset:45120
	ds_read_b128 v[86:89], v1 offset:45136
	ds_read_b128 v[226:229], v1 offset:45152
	s_waitcnt lgkmcnt(0)
	v_fmac_f32_e32 v17, v45, v16
	v_pk_fma_f32 v[18:19], v[46:47], v[16:17], v[18:19] op_sel:[0,0,0] op_sel_hi:[1,0,1]
	v_pk_fma_f32 v[20:21], v[48:49], v[16:17], v[20:21] op_sel:[0,0,0] op_sel_hi:[1,0,1]
	v_pk_fma_f32 v[22:23], v[50:51], v[16:17], v[22:23] op_sel:[0,0,0] op_sel_hi:[1,0,1]
	v_pk_fma_f32 v[24:25], v[52:53], v[16:17], v[24:25] op_sel:[0,0,0] op_sel_hi:[1,0,1]
	v_pk_fma_f32 v[26:27], v[54:55], v[16:17], v[26:27] op_sel:[0,0,0] op_sel_hi:[1,0,1]
	v_pk_fma_f32 v[28:29], v[56:57], v[16:17], v[28:29] op_sel:[0,0,0] op_sel_hi:[1,0,1]
	v_pk_fma_f32 v[30:31], v[58:59], v[16:17], v[30:31] op_sel:[0,0,0] op_sel_hi:[1,0,1]
	v_pk_fma_f32 v[32:33], v[60:61], v[16:17], v[32:33] op_sel:[0,0,0] op_sel_hi:[1,0,1]
	v_pk_fma_f32 v[34:35], v[62:63], v[16:17], v[34:35] op_sel:[0,0,0] op_sel_hi:[1,0,1]
	v_pk_fma_f32 v[36:37], v[64:65], v[16:17], v[36:37] op_sel:[0,0,0] op_sel_hi:[1,0,1]
	v_pk_fma_f32 v[38:39], v[66:67], v[16:17], v[38:39] op_sel:[0,0,0] op_sel_hi:[1,0,1]
	v_pk_fma_f32 v[40:41], v[68:69], v[16:17], v[40:41] op_sel:[0,0,0] op_sel_hi:[1,0,1]
	v_pk_fma_f32 v[18:19], v[70:71], v[16:17], v[18:19] op_sel:[0,1,0] op_sel_hi:[1,1,1]
	v_pk_fma_f32 v[20:21], v[72:73], v[16:17], v[20:21] op_sel:[0,1,0] op_sel_hi:[1,1,1]
	v_pk_fma_f32 v[22:23], v[74:75], v[16:17], v[22:23] op_sel:[0,1,0] op_sel_hi:[1,1,1]
	v_pk_fma_f32 v[24:25], v[76:77], v[16:17], v[24:25] op_sel:[0,1,0] op_sel_hi:[1,1,1]
	v_pk_fma_f32 v[26:27], v[78:79], v[16:17], v[26:27] op_sel:[0,1,0] op_sel_hi:[1,1,1]
	v_pk_fma_f32 v[28:29], v[80:81], v[16:17], v[28:29] op_sel:[0,1,0] op_sel_hi:[1,1,1]
	v_pk_fma_f32 v[30:31], v[82:83], v[16:17], v[30:31] op_sel:[0,1,0] op_sel_hi:[1,1,1]
	v_pk_fma_f32 v[32:33], v[84:85], v[16:17], v[32:33] op_sel:[0,1,0] op_sel_hi:[1,1,1]
	v_pk_fma_f32 v[34:35], v[86:87], v[16:17], v[34:35] op_sel:[0,1,0] op_sel_hi:[1,1,1]
	v_pk_fma_f32 v[36:37], v[88:89], v[16:17], v[36:37] op_sel:[0,1,0] op_sel_hi:[1,1,1]
	v_pk_fma_f32 v[38:39], v[226:227], v[16:17], v[38:39] op_sel:[0,1,0] op_sel_hi:[1,1,1]
	v_pk_fma_f32 v[40:41], v[228:229], v[16:17], v[40:41] op_sel:[0,1,0] op_sel_hi:[1,1,1]
	ds_read_b128 v[42:45], v1 offset:45216
	ds_read_b128 v[46:49], v1 offset:45232
	ds_read_b128 v[50:53], v1 offset:45248
	ds_read_b128 v[54:57], v1 offset:45264
	ds_read_b128 v[58:61], v1 offset:45280
	ds_read_b128 v[62:65], v1 offset:45296
	ds_read_b128 v[66:69], v1 offset:45360
	ds_read_b128 v[70:73], v1 offset:45376
	ds_read_b128 v[74:77], v1 offset:45392
	ds_read_b128 v[78:81], v1 offset:45408
	ds_read_b128 v[82:85], v1 offset:45424
	ds_read_b128 v[86:89], v1 offset:45440
	s_waitcnt lgkmcnt(0)
	v_fmac_f32_e32 v19, v43, v18
	v_pk_fma_f32 v[20:21], v[44:45], v[18:19], v[20:21] op_sel:[0,0,0] op_sel_hi:[1,0,1]
	v_pk_fma_f32 v[22:23], v[46:47], v[18:19], v[22:23] op_sel:[0,0,0] op_sel_hi:[1,0,1]
	v_pk_fma_f32 v[24:25], v[48:49], v[18:19], v[24:25] op_sel:[0,0,0] op_sel_hi:[1,0,1]
	v_pk_fma_f32 v[26:27], v[50:51], v[18:19], v[26:27] op_sel:[0,0,0] op_sel_hi:[1,0,1]
	v_pk_fma_f32 v[28:29], v[52:53], v[18:19], v[28:29] op_sel:[0,0,0] op_sel_hi:[1,0,1]
	v_pk_fma_f32 v[30:31], v[54:55], v[18:19], v[30:31] op_sel:[0,0,0] op_sel_hi:[1,0,1]
	v_pk_fma_f32 v[32:33], v[56:57], v[18:19], v[32:33] op_sel:[0,0,0] op_sel_hi:[1,0,1]
	v_pk_fma_f32 v[34:35], v[58:59], v[18:19], v[34:35] op_sel:[0,0,0] op_sel_hi:[1,0,1]
	v_pk_fma_f32 v[36:37], v[60:61], v[18:19], v[36:37] op_sel:[0,0,0] op_sel_hi:[1,0,1]
	v_pk_fma_f32 v[38:39], v[62:63], v[18:19], v[38:39] op_sel:[0,0,0] op_sel_hi:[1,0,1]
	v_pk_fma_f32 v[40:41], v[64:65], v[18:19], v[40:41] op_sel:[0,0,0] op_sel_hi:[1,0,1]
	v_pk_fma_f32 v[20:21], v[68:69], v[18:19], v[20:21] op_sel:[0,1,0] op_sel_hi:[1,1,1]
	v_pk_fma_f32 v[22:23], v[70:71], v[18:19], v[22:23] op_sel:[0,1,0] op_sel_hi:[1,1,1]
	v_pk_fma_f32 v[24:25], v[72:73], v[18:19], v[24:25] op_sel:[0,1,0] op_sel_hi:[1,1,1]
	v_pk_fma_f32 v[26:27], v[74:75], v[18:19], v[26:27] op_sel:[0,1,0] op_sel_hi:[1,1,1]
	v_pk_fma_f32 v[28:29], v[76:77], v[18:19], v[28:29] op_sel:[0,1,0] op_sel_hi:[1,1,1]
	v_pk_fma_f32 v[30:31], v[78:79], v[18:19], v[30:31] op_sel:[0,1,0] op_sel_hi:[1,1,1]
	v_pk_fma_f32 v[32:33], v[80:81], v[18:19], v[32:33] op_sel:[0,1,0] op_sel_hi:[1,1,1]
	v_pk_fma_f32 v[34:35], v[82:83], v[18:19], v[34:35] op_sel:[0,1,0] op_sel_hi:[1,1,1]
	v_pk_fma_f32 v[36:37], v[84:85], v[18:19], v[36:37] op_sel:[0,1,0] op_sel_hi:[1,1,1]
	v_pk_fma_f32 v[38:39], v[86:87], v[18:19], v[38:39] op_sel:[0,1,0] op_sel_hi:[1,1,1]
	v_pk_fma_f32 v[40:41], v[88:89], v[18:19], v[40:41] op_sel:[0,1,0] op_sel_hi:[1,1,1]
	ds_read_b128 v[42:45], v1 offset:45504
	ds_read_b128 v[46:49], v1 offset:45520
	ds_read_b128 v[50:53], v1 offset:45536
	ds_read_b128 v[54:57], v1 offset:45552
	ds_read_b128 v[58:61], v1 offset:45568
	ds_read_b128 v[62:65], v1 offset:45584
	ds_read_b128 v[66:69], v1 offset:45664
	ds_read_b128 v[70:73], v1 offset:45680
	ds_read_b128 v[74:77], v1 offset:45696
	ds_read_b128 v[78:81], v1 offset:45712
	ds_read_b128 v[82:85], v1 offset:45728
	s_waitcnt lgkmcnt(0)
	v_fmac_f32_e32 v21, v45, v20
	v_pk_fma_f32 v[22:23], v[46:47], v[20:21], v[22:23] op_sel:[0,0,0] op_sel_hi:[1,0,1]
	v_pk_fma_f32 v[24:25], v[48:49], v[20:21], v[24:25] op_sel:[0,0,0] op_sel_hi:[1,0,1]
	v_pk_fma_f32 v[26:27], v[50:51], v[20:21], v[26:27] op_sel:[0,0,0] op_sel_hi:[1,0,1]
	v_pk_fma_f32 v[28:29], v[52:53], v[20:21], v[28:29] op_sel:[0,0,0] op_sel_hi:[1,0,1]
	v_pk_fma_f32 v[30:31], v[54:55], v[20:21], v[30:31] op_sel:[0,0,0] op_sel_hi:[1,0,1]
	v_pk_fma_f32 v[32:33], v[56:57], v[20:21], v[32:33] op_sel:[0,0,0] op_sel_hi:[1,0,1]
	v_pk_fma_f32 v[34:35], v[58:59], v[20:21], v[34:35] op_sel:[0,0,0] op_sel_hi:[1,0,1]
	v_pk_fma_f32 v[36:37], v[60:61], v[20:21], v[36:37] op_sel:[0,0,0] op_sel_hi:[1,0,1]
	v_pk_fma_f32 v[38:39], v[62:63], v[20:21], v[38:39] op_sel:[0,0,0] op_sel_hi:[1,0,1]
	v_pk_fma_f32 v[40:41], v[64:65], v[20:21], v[40:41] op_sel:[0,0,0] op_sel_hi:[1,0,1]
	v_pk_fma_f32 v[22:23], v[66:67], v[20:21], v[22:23] op_sel:[0,1,0] op_sel_hi:[1,1,1]
	v_pk_fma_f32 v[24:25], v[68:69], v[20:21], v[24:25] op_sel:[0,1,0] op_sel_hi:[1,1,1]
	v_pk_fma_f32 v[26:27], v[70:71], v[20:21], v[26:27] op_sel:[0,1,0] op_sel_hi:[1,1,1]
	v_pk_fma_f32 v[28:29], v[72:73], v[20:21], v[28:29] op_sel:[0,1,0] op_sel_hi:[1,1,1]
	v_pk_fma_f32 v[30:31], v[74:75], v[20:21], v[30:31] op_sel:[0,1,0] op_sel_hi:[1,1,1]
	v_pk_fma_f32 v[32:33], v[76:77], v[20:21], v[32:33] op_sel:[0,1,0] op_sel_hi:[1,1,1]
	v_pk_fma_f32 v[34:35], v[78:79], v[20:21], v[34:35] op_sel:[0,1,0] op_sel_hi:[1,1,1]
	v_pk_fma_f32 v[36:37], v[80:81], v[20:21], v[36:37] op_sel:[0,1,0] op_sel_hi:[1,1,1]
	v_pk_fma_f32 v[38:39], v[82:83], v[20:21], v[38:39] op_sel:[0,1,0] op_sel_hi:[1,1,1]
	v_pk_fma_f32 v[40:41], v[84:85], v[20:21], v[40:41] op_sel:[0,1,0] op_sel_hi:[1,1,1]
	ds_read_b128 v[42:45], v1 offset:45808
	ds_read_b128 v[46:49], v1 offset:45824
	ds_read_b128 v[50:53], v1 offset:45840
	ds_read_b128 v[54:57], v1 offset:45856
	ds_read_b128 v[58:61], v1 offset:45872
	ds_read_b128 v[62:65], v1 offset:45952
	ds_read_b128 v[66:69], v1 offset:45968
	ds_read_b128 v[70:73], v1 offset:45984
	ds_read_b128 v[74:77], v1 offset:46000
	ds_read_b128 v[78:81], v1 offset:46016
	s_waitcnt lgkmcnt(0)
	v_fmac_f32_e32 v23, v43, v22
	v_pk_fma_f32 v[24:25], v[44:45], v[22:23], v[24:25] op_sel:[0,0,0] op_sel_hi:[1,0,1]
	v_pk_fma_f32 v[26:27], v[46:47], v[22:23], v[26:27] op_sel:[0,0,0] op_sel_hi:[1,0,1]
	v_pk_fma_f32 v[28:29], v[48:49], v[22:23], v[28:29] op_sel:[0,0,0] op_sel_hi:[1,0,1]
	v_pk_fma_f32 v[30:31], v[50:51], v[22:23], v[30:31] op_sel:[0,0,0] op_sel_hi:[1,0,1]
	v_pk_fma_f32 v[32:33], v[52:53], v[22:23], v[32:33] op_sel:[0,0,0] op_sel_hi:[1,0,1]
	v_pk_fma_f32 v[34:35], v[54:55], v[22:23], v[34:35] op_sel:[0,0,0] op_sel_hi:[1,0,1]
	v_pk_fma_f32 v[36:37], v[56:57], v[22:23], v[36:37] op_sel:[0,0,0] op_sel_hi:[1,0,1]
	v_pk_fma_f32 v[38:39], v[58:59], v[22:23], v[38:39] op_sel:[0,0,0] op_sel_hi:[1,0,1]
	v_pk_fma_f32 v[40:41], v[60:61], v[22:23], v[40:41] op_sel:[0,0,0] op_sel_hi:[1,0,1]
	v_pk_fma_f32 v[24:25], v[64:65], v[22:23], v[24:25] op_sel:[0,1,0] op_sel_hi:[1,1,1]
	v_pk_fma_f32 v[26:27], v[66:67], v[22:23], v[26:27] op_sel:[0,1,0] op_sel_hi:[1,1,1]
	v_pk_fma_f32 v[28:29], v[68:69], v[22:23], v[28:29] op_sel:[0,1,0] op_sel_hi:[1,1,1]
	v_pk_fma_f32 v[30:31], v[70:71], v[22:23], v[30:31] op_sel:[0,1,0] op_sel_hi:[1,1,1]
	v_pk_fma_f32 v[32:33], v[72:73], v[22:23], v[32:33] op_sel:[0,1,0] op_sel_hi:[1,1,1]
	v_pk_fma_f32 v[34:35], v[74:75], v[22:23], v[34:35] op_sel:[0,1,0] op_sel_hi:[1,1,1]
	v_pk_fma_f32 v[36:37], v[76:77], v[22:23], v[36:37] op_sel:[0,1,0] op_sel_hi:[1,1,1]
	v_pk_fma_f32 v[38:39], v[78:79], v[22:23], v[38:39] op_sel:[0,1,0] op_sel_hi:[1,1,1]
	v_pk_fma_f32 v[40:41], v[80:81], v[22:23], v[40:41] op_sel:[0,1,0] op_sel_hi:[1,1,1]
	ds_read_b128 v[42:45], v1 offset:46096
	ds_read_b128 v[46:49], v1 offset:46112
	ds_read_b128 v[50:53], v1 offset:46128
	ds_read_b128 v[54:57], v1 offset:46144
	ds_read_b128 v[58:61], v1 offset:46160
	ds_read_b128 v[62:65], v1 offset:46256
	ds_read_b128 v[66:69], v1 offset:46272
	ds_read_b128 v[70:73], v1 offset:46288
	ds_read_b128 v[74:77], v1 offset:46304
	s_waitcnt lgkmcnt(0)
	v_fmac_f32_e32 v25, v45, v24
	v_pk_fma_f32 v[26:27], v[46:47], v[24:25], v[26:27] op_sel:[0,0,0] op_sel_hi:[1,0,1]
	v_pk_fma_f32 v[28:29], v[48:49], v[24:25], v[28:29] op_sel:[0,0,0] op_sel_hi:[1,0,1]
	v_pk_fma_f32 v[30:31], v[50:51], v[24:25], v[30:31] op_sel:[0,0,0] op_sel_hi:[1,0,1]
	v_pk_fma_f32 v[32:33], v[52:53], v[24:25], v[32:33] op_sel:[0,0,0] op_sel_hi:[1,0,1]
	v_pk_fma_f32 v[34:35], v[54:55], v[24:25], v[34:35] op_sel:[0,0,0] op_sel_hi:[1,0,1]
	v_pk_fma_f32 v[36:37], v[56:57], v[24:25], v[36:37] op_sel:[0,0,0] op_sel_hi:[1,0,1]
	v_pk_fma_f32 v[38:39], v[58:59], v[24:25], v[38:39] op_sel:[0,0,0] op_sel_hi:[1,0,1]
	v_pk_fma_f32 v[40:41], v[60:61], v[24:25], v[40:41] op_sel:[0,0,0] op_sel_hi:[1,0,1]
	v_pk_fma_f32 v[26:27], v[62:63], v[24:25], v[26:27] op_sel:[0,1,0] op_sel_hi:[1,1,1]
	v_pk_fma_f32 v[28:29], v[64:65], v[24:25], v[28:29] op_sel:[0,1,0] op_sel_hi:[1,1,1]
	v_pk_fma_f32 v[30:31], v[66:67], v[24:25], v[30:31] op_sel:[0,1,0] op_sel_hi:[1,1,1]
	v_pk_fma_f32 v[32:33], v[68:69], v[24:25], v[32:33] op_sel:[0,1,0] op_sel_hi:[1,1,1]
	v_pk_fma_f32 v[34:35], v[70:71], v[24:25], v[34:35] op_sel:[0,1,0] op_sel_hi:[1,1,1]
	v_pk_fma_f32 v[36:37], v[72:73], v[24:25], v[36:37] op_sel:[0,1,0] op_sel_hi:[1,1,1]
	v_pk_fma_f32 v[38:39], v[74:75], v[24:25], v[38:39] op_sel:[0,1,0] op_sel_hi:[1,1,1]
	v_pk_fma_f32 v[40:41], v[76:77], v[24:25], v[40:41] op_sel:[0,1,0] op_sel_hi:[1,1,1]
	ds_read_b128 v[42:45], v1 offset:46400
	ds_read_b128 v[46:49], v1 offset:46416
	ds_read_b128 v[50:53], v1 offset:46432
	ds_read_b128 v[54:57], v1 offset:46448
	ds_read_b128 v[58:61], v1 offset:46544
	ds_read_b128 v[62:65], v1 offset:46560
	ds_read_b128 v[66:69], v1 offset:46576
	ds_read_b128 v[70:73], v1 offset:46592
	ds_read_b128 v[74:77], v1 offset:46688
	ds_read_b128 v[78:81], v1 offset:46704
	ds_read_b128 v[82:85], v1 offset:46720
	ds_read_b128 v[86:89], v1 offset:46736
	ds_read_b128 v[226:229], v1 offset:46848
	ds_read_b128 v[230:233], v1 offset:46864
	ds_read_b128 v[234:237], v1 offset:46880
	s_waitcnt lgkmcnt(0)
	v_fmac_f32_e32 v27, v43, v26
	v_pk_fma_f32 v[28:29], v[44:45], v[26:27], v[28:29] op_sel:[0,0,0] op_sel_hi:[1,0,1]
	v_pk_fma_f32 v[30:31], v[46:47], v[26:27], v[30:31] op_sel:[0,0,0] op_sel_hi:[1,0,1]
	v_pk_fma_f32 v[32:33], v[48:49], v[26:27], v[32:33] op_sel:[0,0,0] op_sel_hi:[1,0,1]
	v_pk_fma_f32 v[34:35], v[50:51], v[26:27], v[34:35] op_sel:[0,0,0] op_sel_hi:[1,0,1]
	v_pk_fma_f32 v[36:37], v[52:53], v[26:27], v[36:37] op_sel:[0,0,0] op_sel_hi:[1,0,1]
	v_pk_fma_f32 v[38:39], v[54:55], v[26:27], v[38:39] op_sel:[0,0,0] op_sel_hi:[1,0,1]
	v_pk_fma_f32 v[40:41], v[56:57], v[26:27], v[40:41] op_sel:[0,0,0] op_sel_hi:[1,0,1]
	v_pk_fma_f32 v[28:29], v[60:61], v[26:27], v[28:29] op_sel:[0,1,0] op_sel_hi:[1,1,1]
	v_pk_fma_f32 v[30:31], v[62:63], v[26:27], v[30:31] op_sel:[0,1,0] op_sel_hi:[1,1,1]
	v_pk_fma_f32 v[32:33], v[64:65], v[26:27], v[32:33] op_sel:[0,1,0] op_sel_hi:[1,1,1]
	v_pk_fma_f32 v[34:35], v[66:67], v[26:27], v[34:35] op_sel:[0,1,0] op_sel_hi:[1,1,1]
	v_pk_fma_f32 v[36:37], v[68:69], v[26:27], v[36:37] op_sel:[0,1,0] op_sel_hi:[1,1,1]
	v_pk_fma_f32 v[38:39], v[70:71], v[26:27], v[38:39] op_sel:[0,1,0] op_sel_hi:[1,1,1]
	v_pk_fma_f32 v[40:41], v[72:73], v[26:27], v[40:41] op_sel:[0,1,0] op_sel_hi:[1,1,1]
	v_fmac_f32_e32 v29, v77, v28
	v_pk_fma_f32 v[30:31], v[78:79], v[28:29], v[30:31] op_sel:[0,0,0] op_sel_hi:[1,0,1]
	v_pk_fma_f32 v[32:33], v[80:81], v[28:29], v[32:33] op_sel:[0,0,0] op_sel_hi:[1,0,1]
	v_pk_fma_f32 v[34:35], v[82:83], v[28:29], v[34:35] op_sel:[0,0,0] op_sel_hi:[1,0,1]
	v_pk_fma_f32 v[36:37], v[84:85], v[28:29], v[36:37] op_sel:[0,0,0] op_sel_hi:[1,0,1]
	v_pk_fma_f32 v[38:39], v[86:87], v[28:29], v[38:39] op_sel:[0,0,0] op_sel_hi:[1,0,1]
	v_pk_fma_f32 v[40:41], v[88:89], v[28:29], v[40:41] op_sel:[0,0,0] op_sel_hi:[1,0,1]
	v_pk_fma_f32 v[30:31], v[226:227], v[28:29], v[30:31] op_sel:[0,1,0] op_sel_hi:[1,1,1]
	v_pk_fma_f32 v[32:33], v[228:229], v[28:29], v[32:33] op_sel:[0,1,0] op_sel_hi:[1,1,1]
	v_pk_fma_f32 v[34:35], v[230:231], v[28:29], v[34:35] op_sel:[0,1,0] op_sel_hi:[1,1,1]
	v_pk_fma_f32 v[36:37], v[232:233], v[28:29], v[36:37] op_sel:[0,1,0] op_sel_hi:[1,1,1]
	v_pk_fma_f32 v[38:39], v[234:235], v[28:29], v[38:39] op_sel:[0,1,0] op_sel_hi:[1,1,1]
	v_pk_fma_f32 v[40:41], v[236:237], v[28:29], v[40:41] op_sel:[0,1,0] op_sel_hi:[1,1,1]
	ds_read_b128 v[42:45], v1 offset:46992
	ds_read_b128 v[46:49], v1 offset:47008
	ds_read_b128 v[50:53], v1 offset:47024
	ds_read_b128 v[54:57], v1 offset:47136
	ds_read_b128 v[58:61], v1 offset:47152
	ds_read_b128 v[62:65], v1 offset:47168
	ds_read_b128 v[66:69], v1 offset:47280
	ds_read_b128 v[70:73], v1 offset:47296
	ds_read_b128 v[74:77], v1 offset:47312
	ds_read_b128 v[78:81], v1 offset:47440
	ds_read_b128 v[82:85], v1 offset:47456
	ds_read_b128 v[86:89], v1 offset:47584
	ds_read_b128 v[226:229], v1 offset:47600
	ds_read_b128 v[230:233], v1 offset:47728
	ds_read_b128 v[234:237], v1 offset:47744
	s_waitcnt lgkmcnt(0)
	v_fmac_f32_e32 v31, v43, v30
	v_pk_fma_f32 v[32:33], v[44:45], v[30:31], v[32:33] op_sel:[0,0,0] op_sel_hi:[1,0,1]
	v_pk_fma_f32 v[34:35], v[46:47], v[30:31], v[34:35] op_sel:[0,0,0] op_sel_hi:[1,0,1]
	v_pk_fma_f32 v[36:37], v[48:49], v[30:31], v[36:37] op_sel:[0,0,0] op_sel_hi:[1,0,1]
	v_pk_fma_f32 v[38:39], v[50:51], v[30:31], v[38:39] op_sel:[0,0,0] op_sel_hi:[1,0,1]
	v_pk_fma_f32 v[40:41], v[52:53], v[30:31], v[40:41] op_sel:[0,0,0] op_sel_hi:[1,0,1]
	v_pk_fma_f32 v[32:33], v[56:57], v[30:31], v[32:33] op_sel:[0,1,0] op_sel_hi:[1,1,1]
	v_pk_fma_f32 v[34:35], v[58:59], v[30:31], v[34:35] op_sel:[0,1,0] op_sel_hi:[1,1,1]
	v_pk_fma_f32 v[36:37], v[60:61], v[30:31], v[36:37] op_sel:[0,1,0] op_sel_hi:[1,1,1]
	v_pk_fma_f32 v[38:39], v[62:63], v[30:31], v[38:39] op_sel:[0,1,0] op_sel_hi:[1,1,1]
	v_pk_fma_f32 v[40:41], v[64:65], v[30:31], v[40:41] op_sel:[0,1,0] op_sel_hi:[1,1,1]
	v_fmac_f32_e32 v33, v69, v32
	v_pk_fma_f32 v[34:35], v[70:71], v[32:33], v[34:35] op_sel:[0,0,0] op_sel_hi:[1,0,1]
	v_pk_fma_f32 v[36:37], v[72:73], v[32:33], v[36:37] op_sel:[0,0,0] op_sel_hi:[1,0,1]
	v_pk_fma_f32 v[38:39], v[74:75], v[32:33], v[38:39] op_sel:[0,0,0] op_sel_hi:[1,0,1]
	v_pk_fma_f32 v[40:41], v[76:77], v[32:33], v[40:41] op_sel:[0,0,0] op_sel_hi:[1,0,1]
	v_pk_fma_f32 v[34:35], v[78:79], v[32:33], v[34:35] op_sel:[0,1,0] op_sel_hi:[1,1,1]
	v_pk_fma_f32 v[36:37], v[80:81], v[32:33], v[36:37] op_sel:[0,1,0] op_sel_hi:[1,1,1]
	v_pk_fma_f32 v[38:39], v[82:83], v[32:33], v[38:39] op_sel:[0,1,0] op_sel_hi:[1,1,1]
	v_pk_fma_f32 v[40:41], v[84:85], v[32:33], v[40:41] op_sel:[0,1,0] op_sel_hi:[1,1,1]
	v_fmac_f32_e32 v35, v87, v34
	v_pk_fma_f32 v[36:37], v[88:89], v[34:35], v[36:37] op_sel:[0,0,0] op_sel_hi:[1,0,1]
	v_pk_fma_f32 v[38:39], v[226:227], v[34:35], v[38:39] op_sel:[0,0,0] op_sel_hi:[1,0,1]
	v_pk_fma_f32 v[40:41], v[228:229], v[34:35], v[40:41] op_sel:[0,0,0] op_sel_hi:[1,0,1]
	v_pk_fma_f32 v[36:37], v[232:233], v[34:35], v[36:37] op_sel:[0,1,0] op_sel_hi:[1,1,1]
	v_pk_fma_f32 v[38:39], v[234:235], v[34:35], v[38:39] op_sel:[0,1,0] op_sel_hi:[1,1,1]
	v_pk_fma_f32 v[40:41], v[236:237], v[34:35], v[40:41] op_sel:[0,1,0] op_sel_hi:[1,1,1]
	ds_read_b128 v[42:45], v1 offset:47872
	ds_read_b128 v[46:49], v1 offset:47888
	ds_read_b128 v[50:53], v1 offset:48032
	ds_read_b128 v[54:57], v1 offset:48176
	ds_read_b128 v[58:61], v1 offset:48320
	ds_read_b128 v[62:65], v1 offset:48464
	s_waitcnt lgkmcnt(0)
	v_fmac_f32_e32 v37, v45, v36
	v_pk_fma_f32 v[38:39], v[46:47], v[36:37], v[38:39] op_sel:[0,0,0] op_sel_hi:[1,0,1]
	v_pk_fma_f32 v[40:41], v[48:49], v[36:37], v[40:41] op_sel:[0,0,0] op_sel_hi:[1,0,1]
	v_pk_fma_f32 v[38:39], v[50:51], v[36:37], v[38:39] op_sel:[0,1,0] op_sel_hi:[1,1,1]
	v_pk_fma_f32 v[40:41], v[52:53], v[36:37], v[40:41] op_sel:[0,1,0] op_sel_hi:[1,1,1]
	v_fmac_f32_e32 v39, v55, v38
	v_pk_fma_f32 v[40:41], v[56:57], v[38:39], v[40:41] op_sel:[0,0,0] op_sel_hi:[1,0,1]
	v_pk_fma_f32 v[40:41], v[60:61], v[38:39], v[40:41] op_sel:[0,1,0] op_sel_hi:[1,1,1]
	v_fmac_f32_e32 v41, v65, v40
	ds_write2_b32 v135, v10, v11 offset0:0 offset1:36
	ds_write2_b32 v135, v12, v13 offset0:72 offset1:108
	ds_write2_b32 v135, v14, v15 offset0:144 offset1:180
	ds_write2_b32 v135, v16, v17 offset0:216 offset1:252
	ds_write2_b32 v245, v18, v19 offset0:0 offset1:36
	ds_write2_b32 v245, v20, v21 offset0:72 offset1:108
	ds_write2_b32 v245, v22, v23 offset0:144 offset1:180
	ds_write2_b32 v245, v24, v25 offset0:216 offset1:252
	ds_write2_b32 v246, v26, v27 offset0:0 offset1:36
	ds_write2_b32 v246, v28, v29 offset0:72 offset1:108
	ds_write2_b32 v246, v30, v31 offset0:144 offset1:180
	ds_write2_b32 v246, v32, v33 offset0:216 offset1:252
	ds_write2_b32 v247, v34, v35 offset0:0 offset1:36
	ds_write2_b32 v247, v36, v37 offset0:72 offset1:108
	ds_write2_b32 v247, v38, v39 offset0:144 offset1:180
	ds_write2_b32 v247, v40, v41 offset0:216 offset1:252
	s_mov_b32 exec_hi, -1
	s_branch .Ldc_b3
